# code placement: one 4-byte pad at kernel entry so all eight GEMM MFMA loop heads sit at 0 mod 8 bytes (were at 4 mod 8 after the earlier edits)
# baseline (speedup 1.0000x reference)
; #define LAS __attribute__((address_space(3)))
; __global__ void __launch_bounds__(NTHR, 2) fwd(Args args) {
;     extern __shared__ __attribute__((aligned(16))) unsigned char lds_raw[];
;     Frame F;
;     F.lds = (LAS unsigned char*)lds_raw;
;     F.tid = threadIdx.x; F.lane = F.tid & 63; F.wave = __builtin_amdgcn_readfirstlane(F.tid >> 6);
;     F.G = gridDim.x; F.bid = blockIdx.x;
; #pragma unroll
;     for (int i = 0; i < 12; ++i) F.in[i] = args.in[i];
;     F.out = args.out; F.ws = args.ws;
;     unsigned char* ws = args.ws;
;     bf16* XB = (bf16*)(ws + WS_XB); bf16* BIG = (bf16*)(ws + WS_BIG);
;     const bf16* WIN = (const bf16*)(ws + WS_WIN); const bf16* WOUT = (const bf16*)(ws + WS_WOUT);
;     const bf16* W1 = (const bf16*)(ws + WS_W1); const bf16* W2 = (const bf16*)(ws + WS_W2);
;     const int lo = args.ph_lo, hi = args.ph_hi;
;     ...
;     volatile LAS unsigned* MISC = (volatile LAS unsigned*)(F.lds + 131072 + 64);
;     unsigned* barw = (unsigned*)ws;
;     if (F.tid < 4) MISC[F.tid] = 0u;
;     if (lo == 0 && F.bid == 0) for (int i = F.tid; i < XCD_BAR_WORDS; i += NTHR) barw[i] = 0u;
;     __syncthreads();
_Z3fwd4Args:
	s_nop 0
	s_mov_b32 s98, 1
	v_writelane_b32 v229, s98, 52
	s_load_dword s18, s[0:1], 0x78
	s_load_dwordx8 s[88:95], s[0:1], 0x40
	s_load_dwordx4 s[20:23], s[0:1], 0x60
	s_load_dwordx2 s[80:81], s[0:1], 0x70
	s_add_u32 s4, s0, 0x78
	v_and_b32_e32 v146, 0x3ff, v0
	s_addc_u32 s5, s1, 0
	s_mov_b32 s84, s2
	v_readfirstlane_b32 s3, v146
	v_writelane_b32 v231, s4, 0
	v_cmp_gt_u32_e32 vcc, 4, v146
	s_nop 0
	v_writelane_b32 v231, s5, 1
	s_and_saveexec_b64 s[4:5], vcc
	v_lshl_add_u32 v1, v146, 2, 0
	v_add_u32_e32 v1, 0x20040, v1
	v_mov_b32_e32 v2, 0
	ds_write_b32 v1, v2
	s_or_b64 exec, exec, s[4:5]
	s_load_dwordx16 s[36:51], s[0:1], 0x0
	s_waitcnt lgkmcnt(0)
	s_or_b32 s0, s80, s84
	s_cmp_lg_u32 s0, 0
	s_mov_b32 s4, 0
	v_writelane_b32 v231, s36, 2
	s_nop 1
	v_writelane_b32 v231, s37, 3
	v_writelane_b32 v231, s38, 4
	v_writelane_b32 v231, s39, 5
	v_writelane_b32 v231, s40, 6
	v_writelane_b32 v231, s41, 7
	v_writelane_b32 v231, s42, 8
	v_writelane_b32 v231, s43, 9
	v_writelane_b32 v231, s44, 10
	v_writelane_b32 v231, s45, 11
	v_writelane_b32 v231, s46, 12
	v_writelane_b32 v231, s47, 13
	v_writelane_b32 v231, s48, 14
	v_writelane_b32 v231, s49, 15
	v_writelane_b32 v231, s50, 16
	v_writelane_b32 v231, s51, 17
	s_cbranch_scc1 .LBB0_10
	v_sub_u32_e32 v1, 0xd7f, v146
	v_lshrrev_b32_e32 v2, 9, v1
	v_add_u32_e32 v1, 2, v2
	v_add_u32_e32 v147, 0x200, v146
	v_and_b32_e32 v3, 14, v1
	v_mov_b32_e32 v1, v2
	s_mov_b64 s[6:7], 0
	s_mov_b32 s5, 1
	v_mov_b32_e32 v5, 0
	s_mov_b32 s8, s4
	v_mov_b64_e32 v[6:7], v[146:147]
	s_branch .LBB0_5
